# RG-LRU streaming loads/stores marked nt (keep attention K/V working set in L2)
# speedup vs baseline: 1.0014x; 1.0014x over previous
; #define RG_LOAD(T0) do { _Pragma("unroll") for (int k = 0; k < 4; ++k) { int tk = (T0) + tt - 3 + k; tk = tk < 0 ? 0 : tk; const bf16_t* xp = P.XR + (rowb + tk) * 2048 + cg0; \
;             xr[k][0] = *(const u32x4*)xp; xr[k][1] = *(const u32x4*)(xp + 8); } } while (0)
; __device__ __forceinline__ void rglru_item(const Ptrs& P, unsigned char* lds, int b, int n, int tid) {
;     const int lane = tid & 63, w = __builtin_amdgcn_readfirstlane(tid >> 6), g = lane >> 4, r16 = lane & 15;
;     bf16_t* XCb = (bf16_t*)lds;
;     float* XCf = (float*)(lds + 17408);
;     float* LA = (float*)(lds + 17408 + 32768);
;     float* LB = LA + 8192;
;     const size_t rowb = (size_t)b * T;
;     const int ce = 16 * w + r16, ch = n * 128 + ce;
;     bf16x8 Ba[4], Bx[4];
; #pragma unroll
;     for (int ks = 0; ks < 4; ++ks) { Ba[ks] = *(const bf16x8*)(P.WgaT + (size_t)ch * 128 + 32 * ks + 8 * g); Bx[ks] = *(const bf16x8*)(P.WgxT + (size_t)ch * 128 + 32 * ks + 8 * g); }
;     const float ba = P.bga[ch], bx = P.bgx[ch];
;     const float sp8 = 8.f * log1pf(expf(-P.lam[ch]));
;     const bool big = __any(sp8 > 0.14f);
;     float h = 0.f;
;     const int tt = tid >> 3, c0 = (tid & 7) * 16, cg0 = n * 128 + c0;
;     u32x4 xr[4][2];
;     ...
;     RG_LOAD(0);
.LBB0_450:
	s_cmp_lt_i32 s58, 3
	s_cselect_b64 s[4:5], -1, 0
	s_and_b64 s[40:41], s[4:5], s[0:1]
	s_andn2_b64 vcc, exec, s[40:41]
	s_cbranch_vccnz .LBB0_933
	s_cmp_gt_u32 s2, 63
	v_bfe_u32 v90, v188, 4, 2
	s_cbranch_scc1 .LBB0_460
	v_readfirstlane_b32 s0, v188
	s_lshr_b32 s0, s0, 2
	v_and_b32_e32 v66, 15, v188
	s_and_b32 s0, s0, 0x3ffffff0
	v_or_b32_e32 v67, s0, v66
	s_lshl_b32 s0, s2, 7
	s_and_b32 s1, s0, 0x780
	v_add_u32_e32 v72, s1, v67
	v_mov_b32_e32 v73, 0
	v_lshlrev_b64 v[0:1], 2, v[72:73]
	v_lshl_add_u64 v[2:3], s[22:23], 0, v[0:1]
	global_load_dword v32, v[2:3], off
	s_mov_b32 s5, 0xbfb8aa3b
	s_mov_b32 s7, 0x42ce8ed0
	s_mov_b32 s8, 0xc2b17218
	v_lshlrev_b64 v[2:3], 8, v[72:73]
	v_lshlrev_b32_e32 v64, 4, v90
	v_mov_b32_e32 v68, 0x7f800000
	v_mov_b32_e32 v65, v73
	v_lshl_add_u64 v[4:5], s[64:65], 0, v[2:3]
	v_lshl_add_u64 v[2:3], s[70:71], 0, v[2:3]
	v_lshl_add_u64 v[20:21], v[4:5], 0, v[64:65]
	v_lshl_add_u64 v[28:29], v[2:3], 0, v[64:65]
	s_mov_b32 s9, 0x3f2aaaab
	s_mov_b32 s10, 0x3f317218
	v_mov_b32_e32 v34, 0x3ecc95a3
	s_lshl_b32 s4, s2, 9
	v_lshl_add_u64 v[6:7], s[16:17], 0, v[0:1]
	v_lshl_add_u64 v[0:1], s[20:21], 0, v[0:1]
	v_lshrrev_b32_e32 v93, 3, v188
	s_and_b32 s6, s4, 0x6000
	global_load_dword v91, v[6:7], off
	global_load_dword v92, v[0:1], off
	s_nop 0
	global_load_dwordx4 v[0:3], v[20:21], off
	global_load_dwordx4 v[4:7], v[20:21], off offset:64
	global_load_dwordx4 v[8:11], v[28:29], off
	global_load_dwordx4 v[12:15], v[28:29], off offset:64
	v_sub_u32_e64 v48, v93, 1 clamp
	v_or_b32_e32 v48, s6, v48
	v_or_b32_e32 v94, s6, v93
	v_lshlrev_b32_e32 v48, 12, v48
	v_mov_b32_e32 v49, v73
	v_lshlrev_b32_e32 v56, 12, v94
	v_mov_b32_e32 v57, v73
	s_mov_b32 s0, 0x7f800000
	v_add_u32_e32 v88, 0, v64
	v_lshlrev_b32_e32 v64, 9, v90
	v_add_lshl_u32 v64, v67, v64, 2
	s_add_i32 s4, 0, 0xc400
	v_add_u32_e32 v97, 0, v64
	v_mul_u32_u24_e32 v66, 0x110, v66
	s_mov_b32 s3, 0
	v_lshl_add_u32 v122, v188, 2, s4
	v_add_u32_e32 v124, v88, v66
	v_mov_b32_e32 v125, 0x260
	v_mov_b32_e32 v127, 0
	s_waitcnt vmcnt(0)
	v_mul_f32_e32 v16, 0xbfb8aa3b, v32
	v_fma_f32 v17, v32, s5, -v16
	v_rndne_f32_e32 v18, v16
	v_fmamk_f32 v17, v32, 0xb2a5705f, v17
	v_sub_f32_e32 v16, v16, v18
	v_add_f32_e32 v16, v16, v17
	v_cvt_i32_f32_e32 v33, v18
	v_exp_f32_e32 v35, v16
	v_cmp_nlt_f32_e32 vcc, s7, v32
	global_load_dwordx4 v[16:19], v[20:21], off offset:128
	s_nop 0
	global_load_dwordx4 v[20:23], v[20:21], off offset:192
	s_nop 0
	global_load_dwordx4 v[24:27], v[28:29], off offset:128
	s_nop 0
	global_load_dwordx4 v[28:31], v[28:29], off offset:192
	s_or_b32 s7, s6, 1
	v_ldexp_f32 v33, v35, v33
	v_cndmask_b32_e32 v33, 0, v33, vcc
	v_cmp_ngt_f32_e32 vcc, s8, v32
	s_or_b32 s8, s6, 2
	s_nop 0
	v_cndmask_b32_e32 v65, v68, v33, vcc
	v_add_f32_e32 v35, 1.0, v65
	v_add_f32_e32 v36, -1.0, v35
	v_frexp_mant_f32_e32 v37, v35
	v_cvt_f64_f32_e32 v[32:33], v35
	v_sub_f32_e32 v38, v36, v35
	v_frexp_exp_i32_f64_e32 v32, v[32:33]
	v_cmp_gt_f32_e32 vcc, s9, v37
	v_sub_f32_e32 v36, v65, v36
	v_add_f32_e32 v33, 1.0, v38
	v_subbrev_co_u32_e32 v32, vcc, 0, v32, vcc
	v_add_f32_e32 v33, v36, v33
	v_sub_u32_e32 v36, 0, v32
	v_cvt_f32_i32_e32 v32, v32
	v_ldexp_f32 v35, v35, v36
	v_ldexp_f32 v33, v33, v36
	v_add_f32_e32 v36, -1.0, v35
	v_add_f32_e32 v37, 1.0, v35
	v_add_f32_e32 v38, 1.0, v36
	v_add_f32_e32 v39, -1.0, v37
	v_sub_f32_e32 v38, v35, v38
	v_sub_f32_e32 v35, v35, v39
	v_mul_f32_e32 v39, 0x3f317218, v32
	v_add_f32_e32 v38, v33, v38
	v_add_f32_e32 v33, v33, v35
	v_fma_f32 v35, v32, s10, -v39
	v_add_f32_e32 v40, v36, v38
	v_add_f32_e32 v41, v37, v33
	v_fmamk_f32 v32, v32, 0xb102e308, v35
	v_sub_f32_e32 v35, v36, v40
	v_sub_f32_e32 v36, v37, v41
	v_rcp_f32_e32 v37, v41
	v_add_f32_e32 v42, v39, v32
	v_add_f32_e32 v33, v33, v36
	v_sub_f32_e32 v36, v42, v39
	v_sub_f32_e32 v32, v32, v36
	v_mul_f32_e32 v36, v40, v37
	v_add_f32_e32 v35, v38, v35
	v_mul_f32_e32 v38, v41, v36
	v_fma_f32 v39, v36, v41, -v38
	v_fmac_f32_e32 v39, v36, v33
	v_add_f32_e32 v43, v38, v39
	v_sub_f32_e32 v44, v40, v43
	v_sub_f32_e32 v38, v43, v38
	v_sub_f32_e32 v40, v40, v44
	v_sub_f32_e32 v38, v38, v39
	v_sub_f32_e32 v39, v40, v43
	v_add_f32_e32 v35, v35, v39
	v_add_f32_e32 v35, v38, v35
	v_add_f32_e32 v38, v44, v35
	v_mul_f32_e32 v39, v37, v38
	v_sub_f32_e32 v40, v44, v38
	v_mul_f32_e32 v43, v41, v39
	v_add_f32_e32 v35, v35, v40
	v_add_f32_e32 v40, v36, v39
	v_fma_f32 v41, v39, v41, -v43
	v_sub_f32_e32 v36, v40, v36
	v_fmac_f32_e32 v41, v39, v33
	v_sub_f32_e32 v33, v39, v36
	v_add_f32_e32 v36, v43, v41
	v_sub_f32_e32 v39, v36, v43
	v_sub_f32_e32 v43, v38, v36
	v_sub_f32_e32 v38, v38, v43
	v_sub_f32_e32 v36, v38, v36
	v_sub_f32_e32 v39, v39, v41
	v_add_f32_e32 v35, v35, v36
	v_add_f32_e32 v35, v39, v35
	v_add_f32_e32 v35, v43, v35
	v_mul_f32_e32 v35, v37, v35
	v_add_f32_e32 v33, v33, v35
	v_add_f32_e32 v35, v40, v33
	v_mul_f32_e32 v36, v35, v35
	v_fmac_f32_e32 v34, 0x3e9b6dac, v36
	v_sub_f32_e32 v37, v35, v40
	v_ldexp_f32 v38, v35, 1
	v_mul_f32_e32 v35, v35, v36
	v_fmaak_f32 v34, v36, v34, 0x3f2aaada
	v_mul_f32_e32 v34, v35, v34
	v_add_f32_e32 v35, v38, v34
	v_sub_f32_e32 v33, v33, v37
	v_sub_f32_e32 v36, v35, v38
	v_ldexp_f32 v33, v33, 1
	v_sub_f32_e32 v34, v34, v36
	v_add_f32_e32 v33, v33, v34
	v_add_f32_e32 v34, v35, v33
	v_sub_f32_e32 v35, v34, v35
	v_add_f32_e32 v36, v42, v34
	v_sub_f32_e32 v33, v33, v35
	v_sub_f32_e32 v35, v36, v42
	v_sub_f32_e32 v37, v36, v35
	v_sub_f32_e32 v34, v34, v35
	v_add_f32_e32 v35, v32, v33
	v_sub_f32_e32 v37, v42, v37
	v_sub_f32_e32 v38, v35, v32
	v_add_f32_e32 v34, v34, v37
	v_sub_f32_e32 v37, v35, v38
	v_sub_f32_e32 v33, v33, v38
	v_sub_f32_e32 v32, v32, v37
	v_add_f32_e32 v69, v33, v32
; __device__ __forceinline__ unsigned cvt_pk_bf16(float lo, float hi) { unsigned r; asm volatile("v_cvt_pk_bf16_f32 %0, %1, %2" : "=v"(r) : "v"(lo), "v"(hi)); return r; }
; #define RG_LOAD(T0) do { _Pragma("unroll") for (int k = 0; k < 4; ++k) { int tk = (T0) + tt - 3 + k; tk = tk < 0 ? 0 : tk; const bf16_t* xp = P.XR + (rowb + tk) * 2048 + cg0; \
;             xr[k][0] = *(const u32x4*)xp; xr[k][1] = *(const u32x4*)(xp + 8); } } while (0)
; __device__ __forceinline__ void rglru_item(const Ptrs& P, unsigned char* lds, int b, int n, int tid) {
;     ...
;     RG_LOAD(0);
;     ...
;             bf16_t* gp = P.RG + (rowb + t0 + tt) * 2048 + cg0;
;             const float* hp = LB + tt * 128 + c0;
;             u32x4 o0, o1;
;             o0.x = cvt_pk_bf16(hp[0] * bflo(gc0.x), hp[1] * bfhi(gc0.x)); o0.y = cvt_pk_bf16(hp[2] * bflo(gc0.y), hp[3] * bfhi(gc0.y));
;             o0.z = cvt_pk_bf16(hp[4] * bflo(gc0.z), hp[5] * bfhi(gc0.z)); o0.w = cvt_pk_bf16(hp[6] * bflo(gc0.w), hp[7] * bfhi(gc0.w));
;             o1.x = cvt_pk_bf16(hp[8] * bflo(gc1.x), hp[9] * bfhi(gc1.x)); o1.y = cvt_pk_bf16(hp[10] * bflo(gc1.y), hp[11] * bfhi(gc1.y));
;             o1.z = cvt_pk_bf16(hp[12] * bflo(gc1.z), hp[13] * bfhi(gc1.z)); o1.w = cvt_pk_bf16(hp[14] * bflo(gc1.w), hp[15] * bfhi(gc1.w));
;             *(u32x4*)gp = o0; *(u32x4*)(gp + 8) = o1;
	v_add_f32_e32 v32, v35, v34
	v_add_f32_e32 v70, v36, v32
	v_sub_f32_e32 v33, v70, v36
	v_sub_f32_e32 v71, v32, v33
	v_lshlrev_b32_e32 v32, 4, v188
	v_and_b32_e32 v76, 0x70, v32
	v_or_b32_e32 v77, s1, v76
	v_sub_u32_e64 v32, v93, 3 clamp
	v_sub_u32_e64 v40, v93, 2 clamp
	v_lshlrev_b32_e32 v72, 1, v77
	v_or_b32_e32 v32, s6, v32
	v_or_b32_e32 v40, s6, v40
	v_lshl_add_u64 v[74:75], s[24:25], 0, v[72:73]
	v_lshlrev_b32_e32 v32, 12, v32
	v_mov_b32_e32 v33, v73
	v_lshlrev_b32_e32 v40, 12, v40
	v_mov_b32_e32 v41, v73
	v_lshl_add_u64 v[36:37], v[74:75], 0, v[32:33]
	v_lshl_add_u64 v[44:45], v[74:75], 0, v[40:41]
	v_lshl_add_u64 v[52:53], v[74:75], 0, v[48:49]
	v_lshl_add_u64 v[60:61], v[74:75], 0, v[56:57]
	global_load_dwordx4 v[32:35], v[36:37], off offset:16 nt
	s_nop 0
	global_load_dwordx4 v[36:39], v[36:37], off nt
	s_nop 0
	global_load_dwordx4 v[40:43], v[44:45], off offset:16 nt
	s_nop 0
	global_load_dwordx4 v[44:47], v[44:45], off nt
	s_nop 0
	global_load_dwordx4 v[48:51], v[52:53], off offset:16 nt
	s_nop 0
	global_load_dwordx4 v[52:55], v[52:53], off nt
	s_nop 0
	global_load_dwordx4 v[56:59], v[60:61], off offset:16 nt
	s_nop 0
	global_load_dwordx4 v[60:63], v[60:61], off nt
	v_add_f32_e32 v69, v69, v71
	s_mov_b32 s1, 0x33800000
	v_add_f32_e32 v69, v70, v69
	v_cmp_neq_f32_e32 vcc, s0, v65
	s_add_i32 s0, 0, 0x14400
	v_add_u32_e32 v98, s0, v64
	v_cndmask_b32_e32 v68, v68, v69, vcc
	v_cmp_lt_f32_e64 vcc, |v65|, s1
	v_lshlrev_b32_e32 v69, 2, v76
	s_movk_i32 s1, 0x80
	v_cndmask_b32_e32 v65, v68, v65, vcc
	v_mul_f32_e32 v96, 0xc1000000, v65
	v_add_u32_e32 v65, 0x4000, v64
	v_add_u32_e32 v106, s4, v65
	v_add_u32_e32 v107, s0, v65
	v_add_u32_e32 v65, 0x4200, v64
	v_add_u32_e32 v108, s4, v65
	v_add_u32_e32 v109, s0, v65
	v_add_u32_e32 v65, 0x4400, v64
	v_add_u32_e32 v110, s4, v65
	v_add_u32_e32 v111, s0, v65
	v_add_u32_e32 v65, 0x4600, v64
	v_add_u32_e32 v112, s4, v65
	v_add_u32_e32 v113, s0, v65
	v_add_u32_e32 v65, 0x6000, v64
	v_add_u32_e32 v114, s4, v65
	v_add_u32_e32 v115, s0, v65
	v_add_u32_e32 v65, 0x6200, v64
	v_add_u32_e32 v116, s4, v65
	v_add_u32_e32 v117, s0, v65
	v_add_u32_e32 v65, 0x6400, v64
	v_add_u32_e32 v64, 0x6600, v64
	v_lshlrev_b32_e32 v68, 9, v93
	v_add_u32_e32 v118, s4, v65
	v_add_u32_e32 v119, s0, v65
	v_add_u32_e32 v120, s4, v64
	v_add_u32_e32 v121, s0, v64
	v_lshlrev_b32_e32 v64, 2, v77
	v_mov_b32_e32 v65, v73
	v_add3_u32 v95, 0, v68, v69
	v_add_u32_e32 v69, s0, v69
	v_cmp_gt_u32_e32 vcc, s1, v188
	v_lshl_add_u64 v[78:79], s[46:47], 0, v[64:65]
	s_mov_b64 s[0:1], 0x2000
	v_lshl_add_u64 v[80:81], v[78:79], 0, s[0:1]
	s_mov_b64 s[0:1], 0x4000
	v_lshl_add_u32 v70, v76, 1, 0
	v_mul_u32_u24_e32 v71, 0x110, v93
	v_lshl_add_u64 v[82:83], v[78:79], 0, s[0:1]
	s_mov_b64 s[0:1], 0x6000
	v_add_u32_e32 v99, 0x200, v98
	v_add_u32_e32 v100, 0x400, v98
	v_add_u32_e32 v101, 0x600, v98
	v_add_u32_e32 v102, 0x2000, v98
	v_add_u32_e32 v103, 0x2200, v98
	v_add_u32_e32 v104, 0x2400, v98
	v_add_u32_e32 v105, 0x2600, v98
	v_lshl_add_u64 v[76:77], s[48:49], 0, v[64:65]
	v_lshl_add_u64 v[84:85], v[78:79], 0, s[0:1]
	v_lshl_add_u64 v[86:87], s[26:27], 0, v[72:73]
	s_or_b32 s9, s6, 3
	v_add_u32_e32 v123, v70, v71
	s_mov_b32 s10, 0xf800000
	v_add_u32_e32 v126, v69, v68
	s_branch .LBB0_454
.LBB0_453:
	s_or_b64 exec, exec, s[0:1]
	s_waitcnt lgkmcnt(0)
	s_barrier
	ds_read_b64 v[128:129], v126
	s_waitcnt vmcnt(0)
	v_lshlrev_b32_e32 v72, 16, v68
	v_and_b32_e32 v68, 0xffff0000, v68
	s_add_i32 s3, s3, 1
	s_cmpk_lg_i32 s3, 0x80
	s_waitcnt lgkmcnt(0)
	v_mul_f32_e32 v68, v129, v68
	v_mul_f32_e32 v72, v128, v72
	v_cvt_pk_bf16_f32 v68, v72, v68
	ds_read_b64 v[128:129], v126 offset:8
	v_lshlrev_b32_e32 v72, 16, v69
	v_and_b32_e32 v69, 0xffff0000, v69
	s_waitcnt lgkmcnt(0)
	v_mul_f32_e32 v69, v129, v69
	v_mul_f32_e32 v72, v128, v72
	v_cvt_pk_bf16_f32 v69, v72, v69
	ds_read_b64 v[128:129], v126 offset:16
	v_lshlrev_b32_e32 v72, 16, v70
	v_and_b32_e32 v70, 0xffff0000, v70
	s_waitcnt lgkmcnt(0)
	v_mul_f32_e32 v70, v129, v70
	v_mul_f32_e32 v72, v128, v72
	v_cvt_pk_bf16_f32 v70, v72, v70
	ds_read_b64 v[128:129], v126 offset:24
	v_lshlrev_b32_e32 v72, 16, v71
	v_and_b32_e32 v71, 0xffff0000, v71
	s_waitcnt lgkmcnt(0)
	v_mul_f32_e32 v71, v129, v71
	v_mul_f32_e32 v72, v128, v72
	v_cvt_pk_bf16_f32 v71, v72, v71
	ds_read_b64 v[128:129], v126 offset:32
	v_lshlrev_b32_e32 v72, 16, v64
	v_and_b32_e32 v64, 0xffff0000, v64
	s_waitcnt lgkmcnt(0)
	v_mul_f32_e32 v64, v129, v64
	v_mul_f32_e32 v72, v128, v72
	v_cvt_pk_bf16_f32 v64, v72, v64
	ds_read_b64 v[128:129], v126 offset:40
	v_lshlrev_b32_e32 v72, 16, v65
	v_and_b32_e32 v65, 0xffff0000, v65
	s_waitcnt lgkmcnt(0)
	v_mul_f32_e32 v65, v129, v65
	v_mul_f32_e32 v72, v128, v72
	v_cvt_pk_bf16_f32 v65, v72, v65
	ds_read_b64 v[128:129], v126 offset:48
	v_lshlrev_b32_e32 v72, 16, v66
	v_and_b32_e32 v66, 0xffff0000, v66
	s_waitcnt lgkmcnt(0)
	v_mul_f32_e32 v66, v129, v66
	v_mul_f32_e32 v72, v128, v72
	v_cvt_pk_bf16_f32 v66, v72, v66
	ds_read_b64 v[128:129], v126 offset:56
	v_lshlrev_b32_e32 v72, 16, v67
	v_and_b32_e32 v67, 0xffff0000, v67
	s_waitcnt lgkmcnt(0)
	v_mul_f32_e32 v67, v129, v67
	v_mul_f32_e32 v72, v128, v72
	v_cvt_pk_bf16_f32 v67, v72, v67
	global_store_dwordx4 v[88:89], v[68:71], off nt
	global_store_dwordx4 v[88:89], v[64:67], off offset:16 nt
	s_cbranch_scc0 .LBB0_459
; __device__ __forceinline__ void rglru_item(const Ptrs& P, unsigned char* lds, int b, int n, int tid) {
;     ...
;             for (int e = 0; e < 16; e += 4) { const f32x4 v = *(const f32x4*)(P.conv_b + cg0 + e); xc[e] = v[0]; xc[e + 1] = v[1]; xc[e + 2] = v[2]; xc[e + 3] = v[3]; }
; #pragma unroll
;             for (int k = 0; k < 4; ++k) { const float m = (t0 + tt - 3 + k) >= 0 ? 1.f : 0.f;
;                 float cwk[16];
; #pragma unroll
;                 for (int e = 0; e < 16; e += 4) { const f32x4 c = *(const f32x4*)(P.conv_w + k * 2048 + cg0 + e); cwk[e] = c[0]; cwk[e + 1] = c[1]; cwk[e + 2] = c[2]; cwk[e + 3] = c[3]; }
;                 const u32x4 xa = xr[k][0], xb2 = xr[k][1];
;                 const float xv[16] = {bflo(xa.x), bfhi(xa.x), bflo(xa.y), bfhi(xa.y), bflo(xa.z), bfhi(xa.z), bflo(xa.w), bfhi(xa.w),
;                                       bflo(xb2.x), bfhi(xb2.x), bflo(xb2.y), bfhi(xb2.y), bflo(xb2.z), bfhi(xb2.z), bflo(xb2.w), bfhi(xb2.w)};
; #pragma unroll
;                 for (int e = 0; e < 16; ++e) xc[e] += (cwk[e] * m) * xv[e]; }
.LBB0_454:
	global_load_dwordx4 v[130:133], v[78:79], off
	global_load_dwordx4 v[134:137], v[80:81], off
	global_load_dwordx4 v[138:141], v[82:83], off
	global_load_dwordx4 v[142:145], v[78:79], off offset:16
	global_load_dwordx4 v[146:149], v[80:81], off offset:16
	global_load_dwordx4 v[150:153], v[82:83], off offset:16
	global_load_dwordx4 v[154:157], v[76:77], off
	global_load_dwordx4 v[158:161], v[76:77], off offset:16
	global_load_dwordx4 v[162:165], v[84:85], off
	global_load_dwordx4 v[166:169], v[84:85], off offset:16
	global_load_dwordx4 v[170:173], v[78:79], off offset:32
	global_load_dwordx4 v[174:177], v[76:77], off offset:32
	global_load_dwordx4 v[178:181], v[76:77], off offset:48
	global_load_dwordx4 v[182:185], v[78:79], off offset:48
	global_load_dwordx4 v[190:193], v[80:81], off offset:32
	global_load_dwordx4 v[194:197], v[80:81], off offset:48
	global_load_dwordx4 v[68:71], v[82:83], off offset:48
	global_load_dwordx4 v[198:201], v[82:83], off offset:32
	global_load_dwordx4 v[64:67], v[84:85], off offset:48
	global_load_dwordx4 v[202:205], v[84:85], off offset:32
	s_lshl_b32 s4, s3, 6
	v_add_u32_e32 v128, s4, v93
	v_cmp_lt_u32_e64 s[0:1], 2, v128
	s_waitcnt vmcnt(26)
	v_lshlrev_b32_e32 v88, 16, v36
	v_and_b32_e32 v89, 0xffff0000, v36
	v_cndmask_b32_e64 v72, 0, 1.0, s[0:1]
	v_cmp_lt_u32_e64 s[0:1], 1, v128
	s_waitcnt vmcnt(24)
	v_lshlrev_b32_e32 v186, 16, v44
	v_and_b32_e32 v187, 0xffff0000, v44
	v_cndmask_b32_e64 v234, 0, 1.0, s[0:1]
	v_cmp_eq_u32_e64 s[0:1], 0, v128
	v_lshlrev_b32_e32 v212, 16, v37
	v_and_b32_e32 v213, 0xffff0000, v37
	v_lshlrev_b32_e32 v220, 16, v38
	v_and_b32_e32 v221, 0xffff0000, v38
	v_lshlrev_b32_e32 v228, 16, v39
	v_and_b32_e32 v229, 0xffff0000, v39
	v_cndmask_b32_e64 v236, 1.0, 0, s[0:1]
	s_waitcnt vmcnt(22)
	v_lshlrev_b32_e32 v208, 16, v52
	v_and_b32_e32 v209, 0xffff0000, v52
	v_lshlrev_b32_e32 v214, 16, v45
	v_and_b32_e32 v215, 0xffff0000, v45
	v_lshlrev_b32_e32 v222, 16, v46
	v_and_b32_e32 v223, 0xffff0000, v46
	v_lshlrev_b32_e32 v230, 16, v47
	v_and_b32_e32 v231, 0xffff0000, v47
	s_waitcnt vmcnt(20)
	v_lshlrev_b32_e32 v210, 16, v60
	v_and_b32_e32 v211, 0xffff0000, v60
	v_lshlrev_b32_e32 v216, 16, v53
	v_and_b32_e32 v217, 0xffff0000, v53
	v_lshlrev_b32_e32 v224, 16, v54
	v_and_b32_e32 v225, 0xffff0000, v54
	v_lshlrev_b32_e32 v232, 16, v55
	v_and_b32_e32 v233, 0xffff0000, v55
	v_lshlrev_b32_e32 v218, 16, v61
	v_and_b32_e32 v219, 0xffff0000, v61
	v_lshlrev_b32_e32 v226, 16, v62
	v_and_b32_e32 v227, 0xffff0000, v62
	s_cmpk_eq_i32 s3, 0x7f
	s_waitcnt vmcnt(19)
	v_pk_mul_f32 v[130:131], v[72:73], v[130:131] op_sel_hi:[0,1]
	s_waitcnt vmcnt(18)
	v_pk_mul_f32 v[134:135], v[234:235], v[134:135] op_sel_hi:[0,1]
	v_pk_mul_f32 v[132:133], v[72:73], v[132:133] op_sel_hi:[0,1]
	s_waitcnt vmcnt(16)
	v_pk_mul_f32 v[142:143], v[72:73], v[142:143] op_sel_hi:[0,1]
	v_pk_mul_f32 v[144:145], v[72:73], v[144:145] op_sel_hi:[0,1]
	v_pk_mul_f32 v[138:139], v[236:237], v[138:139] op_sel_hi:[0,1]
	s_waitcnt vmcnt(13)
	v_pk_fma_f32 v[88:89], v[130:131], v[88:89], v[154:155]
	v_pk_mul_f32 v[136:137], v[234:235], v[136:137] op_sel_hi:[0,1]
	v_pk_mul_f32 v[146:147], v[234:235], v[146:147] op_sel_hi:[0,1]
	v_pk_mul_f32 v[148:149], v[234:235], v[148:149] op_sel_hi:[0,1]
	v_pk_fma_f32 v[130:131], v[132:133], v[212:213], v[156:157]
	s_waitcnt vmcnt(12)
	v_pk_fma_f32 v[132:133], v[142:143], v[220:221], v[158:159]
	v_pk_fma_f32 v[142:143], v[144:145], v[228:229], v[160:161]
	v_pk_fma_f32 v[88:89], v[134:135], v[186:187], v[88:89]
	v_pk_mul_f32 v[140:141], v[236:237], v[140:141] op_sel_hi:[0,1]
	v_pk_mul_f32 v[150:151], v[236:237], v[150:151] op_sel_hi:[0,1]
	v_pk_mul_f32 v[152:153], v[236:237], v[152:153] op_sel_hi:[0,1]
	v_pk_fma_f32 v[130:131], v[136:137], v[214:215], v[130:131]
	v_pk_fma_f32 v[132:133], v[146:147], v[222:223], v[132:133]
	v_pk_fma_f32 v[134:135], v[148:149], v[230:231], v[142:143]
	v_pk_fma_f32 v[88:89], v[138:139], v[208:209], v[88:89]
	v_pk_fma_f32 v[136:137], v[140:141], v[216:217], v[130:131]
	v_pk_fma_f32 v[138:139], v[150:151], v[224:225], v[132:133]
	v_pk_fma_f32 v[140:141], v[152:153], v[232:233], v[134:135]
	s_waitcnt vmcnt(11)
	v_pk_fma_f32 v[130:131], v[162:163], v[210:211], v[88:89]
	v_lshlrev_b32_e32 v88, 16, v63
	v_and_b32_e32 v89, 0xffff0000, v63
	v_pk_fma_f32 v[132:133], v[164:165], v[218:219], v[136:137]
	s_waitcnt vmcnt(10)
	v_pk_fma_f32 v[134:135], v[166:167], v[226:227], v[138:139]
	v_pk_fma_f32 v[136:137], v[168:169], v[88:89], v[140:141]
	v_lshlrev_b32_e32 v88, 16, v32
	v_and_b32_e32 v89, 0xffff0000, v32
	s_waitcnt vmcnt(9)
; __device__ __forceinline__ unsigned cvt_pk_bf16(float lo, float hi) { unsigned r; asm volatile("v_cvt_pk_bf16_f32 %0, %1, %2" : "=v"(r) : "v"(lo), "v"(hi)); return r; }
; #define RG_LOAD(T0) do { _Pragma("unroll") for (int k = 0; k < 4; ++k) { int tk = (T0) + tt - 3 + k; tk = tk < 0 ? 0 : tk; const bf16_t* xp = P.XR + (rowb + tk) * 2048 + cg0; \
;             xr[k][0] = *(const u32x4*)xp; xr[k][1] = *(const u32x4*)(xp + 8); } } while (0)
; __device__ __forceinline__ void rglru_item(const Ptrs& P, unsigned char* lds, int b, int n, int tid) {
;     ...
;             for (int e = 0; e < 16; e += 4) { const f32x4 v = *(const f32x4*)(P.conv_b + cg0 + e); xc[e] = v[0]; xc[e + 1] = v[1]; xc[e + 2] = v[2]; xc[e + 3] = v[3]; }
; #pragma unroll
;             for (int k = 0; k < 4; ++k) { const float m = (t0 + tt - 3 + k) >= 0 ? 1.f : 0.f;
;                 float cwk[16];
; #pragma unroll
;                 for (int e = 0; e < 16; e += 4) { const f32x4 c = *(const f32x4*)(P.conv_w + k * 2048 + cg0 + e); cwk[e] = c[0]; cwk[e + 1] = c[1]; cwk[e + 2] = c[2]; cwk[e + 3] = c[3]; }
;                 const u32x4 xa = xr[k][0], xb2 = xr[k][1];
;                 const float xv[16] = {bflo(xa.x), bfhi(xa.x), bflo(xa.y), bfhi(xa.y), bflo(xa.z), bfhi(xa.z), bflo(xa.w), bfhi(xa.w),
;                                       bflo(xb2.x), bfhi(xb2.x), bflo(xb2.y), bfhi(xb2.y), bflo(xb2.z), bfhi(xb2.z), bflo(xb2.w), bfhi(xb2.w)};
; #pragma unroll
;                 for (int e = 0; e < 16; ++e) xc[e] += (cwk[e] * m) * xv[e]; }
; #pragma unroll
;             for (int e = 0; e < 16; e += 4) *(f32x4*)(XCf + tt * 128 + c0 + e) = (f32x4){xc[e], xc[e + 1], xc[e + 2], xc[e + 3]};
;             u32x4 w0, w1; w0.x = cvt_pk_bf16(xc[0], xc[1]); w0.y = cvt_pk_bf16(xc[2], xc[3]); w0.z = cvt_pk_bf16(xc[4], xc[5]); w0.w = cvt_pk_bf16(xc[6], xc[7]);
;             w1.x = cvt_pk_bf16(xc[8], xc[9]); w1.y = cvt_pk_bf16(xc[10], xc[11]); w1.z = cvt_pk_bf16(xc[12], xc[13]); w1.w = cvt_pk_bf16(xc[14], xc[15]);
;             *(u32x4*)(XCb + tt * 136 + c0) = w0; *(u32x4*)(XCb + tt * 136 + c0 + 8) = w1;
;             { const bf16_t* gp_ = P.RG + (rowb + t0 + tt) * 2048 + cg0; gc0 = *(const u32x4*)gp_; gc1 = *(const u32x4*)(gp_ + 8); }
;             if (chunk + 1 < T / 64) RG_LOAD(t0 + 64);
	v_pk_mul_f32 v[138:139], v[72:73], v[170:171] op_sel_hi:[0,1]
	s_waitcnt vmcnt(8)
	v_pk_fma_f32 v[88:89], v[138:139], v[88:89], v[174:175]
	v_lshlrev_b32_e32 v138, 16, v40
	v_and_b32_e32 v139, 0xffff0000, v40
	s_waitcnt vmcnt(5)
	v_pk_mul_f32 v[140:141], v[234:235], v[190:191] op_sel_hi:[0,1]
	v_pk_fma_f32 v[88:89], v[140:141], v[138:139], v[88:89]
	v_lshlrev_b32_e32 v138, 16, v48
	v_and_b32_e32 v139, 0xffff0000, v48
	s_waitcnt vmcnt(2)
	v_pk_mul_f32 v[140:141], v[236:237], v[198:199] op_sel_hi:[0,1]
	v_pk_fma_f32 v[88:89], v[140:141], v[138:139], v[88:89]
	v_lshlrev_b32_e32 v138, 16, v56
	v_and_b32_e32 v139, 0xffff0000, v56
	s_waitcnt vmcnt(0)
	v_pk_fma_f32 v[138:139], v[202:203], v[138:139], v[88:89]
	v_lshlrev_b32_e32 v88, 16, v33
	v_and_b32_e32 v89, 0xffff0000, v33
	v_pk_mul_f32 v[140:141], v[72:73], v[172:173] op_sel_hi:[0,1]
	v_pk_fma_f32 v[88:89], v[140:141], v[88:89], v[176:177]
	v_lshlrev_b32_e32 v140, 16, v41
	v_and_b32_e32 v141, 0xffff0000, v41
	v_pk_mul_f32 v[142:143], v[234:235], v[192:193] op_sel_hi:[0,1]
	v_pk_fma_f32 v[88:89], v[142:143], v[140:141], v[88:89]
	v_lshlrev_b32_e32 v140, 16, v49
	v_and_b32_e32 v141, 0xffff0000, v49
	v_pk_mul_f32 v[142:143], v[236:237], v[200:201] op_sel_hi:[0,1]
	v_pk_fma_f32 v[88:89], v[142:143], v[140:141], v[88:89]
	v_lshlrev_b32_e32 v140, 16, v57
	v_and_b32_e32 v141, 0xffff0000, v57
	v_pk_fma_f32 v[140:141], v[204:205], v[140:141], v[88:89]
	v_lshlrev_b32_e32 v88, 16, v34
	v_and_b32_e32 v89, 0xffff0000, v34
	v_pk_mul_f32 v[142:143], v[72:73], v[182:183] op_sel_hi:[0,1]
	v_pk_fma_f32 v[88:89], v[142:143], v[88:89], v[178:179]
	v_lshlrev_b32_e32 v142, 16, v42
	v_and_b32_e32 v143, 0xffff0000, v42
	v_pk_mul_f32 v[144:145], v[234:235], v[194:195] op_sel_hi:[0,1]
	v_pk_fma_f32 v[88:89], v[144:145], v[142:143], v[88:89]
	v_lshlrev_b32_e32 v142, 16, v50
	v_and_b32_e32 v143, 0xffff0000, v50
	v_pk_mul_f32 v[68:69], v[236:237], v[68:69] op_sel_hi:[0,1]
	v_pk_fma_f32 v[68:69], v[68:69], v[142:143], v[88:89]
	v_lshlrev_b32_e32 v88, 16, v58
	v_and_b32_e32 v89, 0xffff0000, v58
	v_pk_fma_f32 v[64:65], v[64:65], v[88:89], v[68:69]
	v_lshlrev_b32_e32 v68, 16, v35
	v_and_b32_e32 v69, 0xffff0000, v35
	v_pk_mul_f32 v[88:89], v[72:73], v[184:185] op_sel_hi:[0,1]
	v_pk_fma_f32 v[68:69], v[88:89], v[68:69], v[180:181]
	v_lshlrev_b32_e32 v88, 16, v43
	v_and_b32_e32 v89, 0xffff0000, v43
	v_pk_mul_f32 v[142:143], v[234:235], v[196:197] op_sel_hi:[0,1]
	v_pk_fma_f32 v[68:69], v[142:143], v[88:89], v[68:69]
	v_lshlrev_b32_e32 v88, 16, v51
	v_and_b32_e32 v89, 0xffff0000, v51
	v_pk_mul_f32 v[70:71], v[236:237], v[70:71] op_sel_hi:[0,1]
	v_pk_fma_f32 v[68:69], v[70:71], v[88:89], v[68:69]
	v_lshlrev_b32_e32 v70, 16, v59
	v_and_b32_e32 v71, 0xffff0000, v59
	v_add_u32_e32 v72, s4, v94
	v_pk_fma_f32 v[66:67], v[66:67], v[70:71], v[68:69]
	ds_write_b128 v95, v[130:133] offset:17408
	ds_write_b128 v95, v[134:137] offset:17424
	ds_write_b128 v95, v[138:141] offset:17440
	ds_write_b128 v95, v[64:67] offset:17456
	v_cvt_pk_bf16_f32 v130, v130, v131
	v_cvt_pk_bf16_f32 v131, v132, v133
	v_cvt_pk_bf16_f32 v132, v134, v135
	v_cvt_pk_bf16_f32 v133, v136, v137
	v_cvt_pk_bf16_f32 v134, v138, v139
	v_cvt_pk_bf16_f32 v135, v140, v141
	v_cvt_pk_bf16_f32 v136, v64, v65
	v_lshlrev_b64 v[64:65], 12, v[72:73]
	v_lshl_add_u64 v[88:89], v[86:87], 0, v[64:65]
	v_cvt_pk_bf16_f32 v137, v66, v67
	global_load_dwordx4 v[64:67], v[88:89], off offset:16 nt
	global_load_dwordx4 v[68:71], v[88:89], off nt
	ds_write_b128 v123, v[130:133]
	ds_write_b128 v123, v[134:137] offset:16
	s_cbranch_scc1 .LBB0_456
	v_add_u32_e32 v56, 61, v128
	v_add_u32_e32 v72, s6, v56
	v_lshlrev_b64 v[32:33], 12, v[72:73]
	v_add_u32_e32 v72, s7, v56
	v_lshlrev_b64 v[40:41], 12, v[72:73]
	v_add_u32_e32 v72, s8, v56
	v_lshlrev_b64 v[48:49], 12, v[72:73]
	v_add_u32_e32 v72, s9, v56
	v_lshlrev_b64 v[56:57], 12, v[72:73]
	v_lshl_add_u64 v[36:37], v[74:75], 0, v[32:33]
	v_lshl_add_u64 v[44:45], v[74:75], 0, v[40:41]
	v_lshl_add_u64 v[52:53], v[74:75], 0, v[48:49]
	v_lshl_add_u64 v[60:61], v[74:75], 0, v[56:57]
	global_load_dwordx4 v[32:35], v[36:37], off offset:16 nt
	s_nop 0
	global_load_dwordx4 v[36:39], v[36:37], off nt
	s_nop 0
	global_load_dwordx4 v[40:43], v[44:45], off offset:16 nt
	s_nop 0
	global_load_dwordx4 v[44:47], v[44:45], off nt
	s_nop 0
	global_load_dwordx4 v[48:51], v[52:53], off offset:16 nt
	s_nop 0
	global_load_dwordx4 v[52:55], v[52:53], off nt
	s_nop 0
	global_load_dwordx4 v[56:59], v[60:61], off offset:16 nt
	s_nop 0
	global_load_dwordx4 v[60:63], v[60:61], off nt
